# phase0 weight conversion: preload norm gains a half-iteration early, counted vmcnt(6) instead of vmcnt(0) drains
# speedup vs baseline: 1.0035x; 1.0035x over previous
.LBB0_97:
	v_readlane_b32 s36, v250, 0
	s_lshl_b32 s15, s3, 1
	v_readlane_b32 s50, v250, 14
	v_readlane_b32 s51, v250, 15
	s_add_u32 s16, s50, 0x16020000
	v_readlane_b32 s42, v250, 6
	s_addc_u32 s17, s51, 0
	v_readlane_b32 s43, v250, 7
	s_add_u32 s30, s42, 0x1000000
	s_addc_u32 s31, s43, 0
	v_readlane_b32 s68, v250, 21
	s_add_u32 s34, s50, 0x15820000
	v_readlane_b32 s69, v250, 22
	v_readlane_b32 s70, v250, 23
	v_readlane_b32 s71, v250, 24
	v_readlane_b32 s72, v250, 25
	v_readlane_b32 s73, v250, 26
	v_readlane_b32 s74, v250, 27
	v_readlane_b32 s75, v250, 28
	v_readlane_b32 s76, v250, 29
	v_readlane_b32 s77, v250, 30
	v_readlane_b32 s78, v250, 31
	v_readlane_b32 s79, v250, 32
	s_addc_u32 s35, s51, 0
	v_readlane_b32 s80, v250, 33
	v_readlane_b32 s81, v250, 34
	v_readlane_b32 s82, v250, 35
	v_readlane_b32 s83, v250, 36
	s_mov_b64 s[68:69], s[72:73]
	v_readlane_b32 s37, v250, 1
	s_add_u32 s36, s68, 0x6000
	s_addc_u32 s37, s69, 0
	s_add_u32 s52, s50, 0x14820000
	s_addc_u32 s53, s51, 0
	s_add_u32 s54, s50, 0x14020000
	s_addc_u32 s55, s51, 0
	s_add_u32 s56, s68, 0x4000
	s_addc_u32 s57, s69, 0
	v_lshlrev_b32_e32 v1, 2, v34
	s_add_u32 s18, s50, 0xc020000
	v_and_b32_e32 v36, 60, v1
	v_and_b32_e32 v1, 15, v34
	s_addc_u32 s19, s51, 0
	v_lshl_add_u32 v48, v1, 4, 0
	v_lshlrev_b32_e32 v38, 3, v1
	v_add_u32_e32 v1, 0x200, v34
	s_add_u32 s20, s50, 0x4020000
	v_ashrrev_i32_e32 v40, 4, v34
	s_movk_i32 s10, 0x104
	v_ashrrev_i32_e32 v44, 4, v1
	v_ashrrev_i32_e32 v34, 3, v34
	s_addc_u32 s21, s51, 0
	v_mul_lo_u32 v49, v40, s10
	v_lshlrev_b32_e32 v42, 1, v40
	v_lshl_add_u32 v50, v40, 2, 0
	v_mul_u32_u24_e32 v51, 0x104, v36
	v_lshlrev_b32_e32 v46, 1, v44
	v_lshl_add_u32 v53, v44, 2, 0
	v_and_b32_e32 v41, -2, v34
	v_ashrrev_i32_e32 v1, 3, v1
	v_mul_lo_u32 v34, v44, s10
	s_add_u32 s22, s50, 0x3020000
	v_mov_b32_e32 v35, 0
	s_mov_b32 s11, 0
	v_ashrrev_i32_e32 v43, 31, v42
	v_ashrrev_i32_e32 v47, 31, v46
	v_and_b32_e32 v45, -2, v1
	v_ashrrev_i32_e32 v1, 31, v40
	v_ashrrev_i32_e32 v37, 31, v44
	s_addc_u32 s23, s51, 0
	s_mul_i32 s24, s3, 3
	v_add_u32_e32 v52, v50, v51
	v_add_u32_e32 v53, v53, v51
	v_add_u32_e32 v54, v48, v49
	v_add_u32_e32 v55, v48, v34
	s_mov_b32 s27, s2
	v_readlane_b32 s38, v250, 2
	v_readlane_b32 s39, v250, 3
	v_readlane_b32 s40, v250, 4
	v_readlane_b32 s41, v250, 5
	v_readlane_b32 s44, v250, 8
	v_readlane_b32 s45, v250, 9
	v_readlane_b32 s46, v250, 10
	v_readlane_b32 s47, v250, 11
	v_readlane_b32 s48, v250, 12
	v_readlane_b32 s49, v250, 13
	s_mov_b64 s[70:71], s[74:75]
	s_mov_b64 s[72:73], s[76:77]
	s_mov_b64 s[74:75], s[78:79]
	s_mov_b64 s[76:77], s[80:81]
	s_mov_b64 s[78:79], s[82:83]
	v_mov_b32_e32 v240, 1.0
	v_mov_b32_e32 v241, 1.0
	v_mov_b32_e32 v242, 1.0
	v_mov_b32_e32 v243, 1.0
	s_cmp_eq_u64 s[4:5], 0
	s_cbranch_scc1 .Lcv_pre_a0
	v_lshl_add_u64 v[238:239], v[42:43], 2, s[4:5]
	global_load_dwordx2 v[240:241], v[238:239], off
	v_lshl_add_u64 v[238:239], v[46:47], 2, s[4:5]
	global_load_dwordx2 v[242:243], v[238:239], off
.Lcv_pre_a0:
	s_waitcnt vmcnt(0)
	s_branch .LBB0_101

.LBB0_101:
	s_waitcnt vmcnt(6)
	v_mov_b32_e32 v48, v242
	v_mov_b32_e32 v50, v240
	v_mov_b32_e32 v51, v241
.LBB0_103:
	v_mul_f32_e32 v34, 0x3e0293ee, v50
	v_mul_f32_e32 v49, 0x3e0293ee, v51
	v_cndmask_b32_e64 v49, v51, v49, s[0:1]
	v_cndmask_b32_e64 v34, v50, v34, s[0:1]
	v_mul_f32_e32 v50, v6, v34
	v_mul_f32_e32 v51, v2, v49
	v_cvt_pk_bf16_f32 v50, v50, v51
	v_mul_f32_e32 v51, v7, v34
	v_mul_f32_e32 v56, v3, v49
	v_cvt_pk_bf16_f32 v51, v51, v56
	ds_write2_b32 v52, v50, v51 offset1:65
	v_mul_f32_e32 v50, v8, v34
	v_mul_f32_e32 v51, v4, v49
	v_mul_f32_e32 v34, v9, v34
	v_mul_f32_e32 v49, v5, v49
	v_cvt_pk_bf16_f32 v50, v50, v51
	v_cvt_pk_bf16_f32 v34, v34, v49
	v_mov_b32_e32 v49, v243
	ds_write2_b32 v52, v50, v34 offset0:130 offset1:195
.LBB0_105:
	v_mul_f32_e32 v34, 0x3e0293ee, v48
	v_mul_f32_e32 v50, 0x3e0293ee, v49
	v_cndmask_b32_e64 v49, v49, v50, s[0:1]
	v_cndmask_b32_e64 v34, v48, v34, s[0:1]
	v_mul_f32_e32 v48, v14, v34
	v_mul_f32_e32 v50, v10, v49
	v_cvt_pk_bf16_f32 v48, v48, v50
	v_mul_f32_e32 v50, v15, v34
	v_mul_f32_e32 v51, v11, v49
	s_add_i32 s25, s27, s15
	v_cvt_pk_bf16_f32 v50, v50, v51
	s_cmpk_gt_i32 s25, 0x5bff
	ds_write2_b32 v53, v48, v50 offset1:65
	v_mul_f32_e32 v48, v16, v34
	v_mul_f32_e32 v50, v12, v49
	v_mul_f32_e32 v34, v17, v34
	v_mul_f32_e32 v49, v13, v49
	s_cselect_b64 s[60:61], -1, 0
	v_cvt_pk_bf16_f32 v48, v48, v50
	v_cvt_pk_bf16_f32 v34, v34, v49
	s_and_b64 vcc, exec, s[60:61]
	s_mov_b64 s[66:67], s[58:59]
	s_mov_b32 s26, s14
	ds_write2_b32 v53, v48, v34 offset0:130 offset1:195
	v_mov_b32_e32 v244, 1.0
	v_mov_b32_e32 v245, 1.0
	v_mov_b32_e32 v246, 1.0
	v_mov_b32_e32 v247, 1.0
	s_cmp_eq_u64 s[64:65], 0
	s_cbranch_scc1 .Lcv_pre_b
	v_lshl_add_u64 v[238:239], v[42:43], 2, s[64:65]
	global_load_dwordx2 v[244:245], v[238:239], off
	v_lshl_add_u64 v[238:239], v[46:47], 2, s[64:65]
	global_load_dwordx2 v[246:247], v[238:239], off
.Lcv_pre_b:
	s_cbranch_vccnz .Lcv_skip_a
	s_cmpk_gt_i32 s25, 0xbff
	s_mov_b64 s[70:71], -1
	s_cbranch_scc0 .LBB0_130
	s_cmpk_gt_u32 s25, 0xfff
	s_cbranch_scc0 .LBB0_127
	s_cmpk_gt_u32 s25, 0x2fff
	s_cbranch_scc0 .LBB0_124
	s_cmpk_gt_u32 s25, 0x4fff
	s_cbranch_scc0 .LBB0_121
	s_cmpk_gt_u32 s25, 0x51ff
	s_cbranch_scc0 .LBB0_118
	s_cmpk_gt_u32 s25, 0x55ff
	s_cbranch_scc0 .LBB0_151
	s_cmpk_gt_u32 s25, 0x57ff
	s_mov_b64 s[68:69], -1
	s_cbranch_scc0 .LBB0_114
	s_add_i32 s0, s25, 0xffffa800
	s_lshr_b32 s10, s0, 9
	v_readlane_b32 s68, v250, 0
	s_and_b32 s28, s25, 0x1ff
	s_lshl_b64 s[0:1], s[10:11], 24
	v_readlane_b32 s76, v250, 8
	v_readlane_b32 s77, v250, 9
	s_add_u32 s4, s76, s0
	s_addc_u32 s5, s77, s1
	s_lshl_b64 s[0:1], s[10:11], 23
	v_readlane_b32 s69, v250, 1
	s_add_u32 s0, s16, s0
	v_readlane_b32 s70, v250, 2
	v_readlane_b32 s71, v250, 3
	v_readlane_b32 s72, v250, 4
	v_readlane_b32 s73, v250, 5
	v_readlane_b32 s74, v250, 6
	v_readlane_b32 s75, v250, 7
	v_readlane_b32 s78, v250, 10
	v_readlane_b32 s79, v250, 11
	v_readlane_b32 s80, v250, 12
	v_readlane_b32 s81, v250, 13
	v_readlane_b32 s82, v250, 14
	v_readlane_b32 s83, v250, 15
	s_addc_u32 s1, s17, s1
	s_mov_b64 s[68:69], 0

.LBB0_133:
	s_waitcnt lgkmcnt(0)
	s_barrier
	ds_read2_b32 v[48:49], v54 offset1:1
	ds_read2_b32 v[50:51], v54 offset0:2 offset1:3
	v_mad_u64_u32 v[56:57], s[28:29], s14, v40, 0
	v_mov_b32_e32 v58, v57
	v_lshlrev_b32_e32 v34, 1, v38
	v_mad_u64_u32 v[58:59], s[28:29], s14, v1, v[58:59]
	v_lshl_add_u64 v[60:61], s[58:59], 0, v[34:35]
	v_mov_b32_e32 v57, v58
	v_lshl_add_u64 v[62:63], v[56:57], 1, v[60:61]
	ds_read2_b32 v[56:57], v55 offset1:1
	ds_read2_b32 v[58:59], v55 offset0:2 offset1:3
	s_waitcnt lgkmcnt(2)
	global_store_dwordx4 v[62:63], v[48:51], off
	s_add_i32 s33, s27, s3
	s_cmpk_gt_i32 s33, 0x5bff
	v_mad_u64_u32 v[48:49], s[28:29], s14, v44, 0
	v_mov_b32_e32 v50, v49
	v_mad_u64_u32 v[50:51], s[28:29], s14, v37, v[50:51]
	v_mov_b32_e32 v49, v50
	v_lshl_add_u64 v[48:49], v[48:49], 1, v[60:61]
	s_mov_b64 s[58:59], -1
	s_waitcnt lgkmcnt(0)
	global_store_dwordx4 v[48:49], v[56:59], off
	s_barrier
	s_cbranch_scc1 .LBB0_100
	s_waitcnt vmcnt(6)
	v_mov_b32_e32 v48, v246
	v_mov_b32_e32 v50, v244
	v_mov_b32_e32 v51, v245
.LBB0_136:
	v_mul_f32_e32 v49, 0x3e0293ee, v50
	v_mul_f32_e32 v56, 0x3e0293ee, v51
	v_cndmask_b32_e64 v49, v50, v49, s[62:63]
	v_cndmask_b32_e64 v50, v51, v56, s[62:63]
	v_mul_f32_e32 v51, v22, v49
	v_mul_f32_e32 v56, v18, v50
	v_cvt_pk_bf16_f32 v51, v51, v56
	v_mul_f32_e32 v56, v23, v49
	v_mul_f32_e32 v57, v19, v50
	v_cvt_pk_bf16_f32 v56, v56, v57
	ds_write2_b32 v52, v51, v56 offset1:65
	v_mul_f32_e32 v51, v24, v49
	v_mul_f32_e32 v56, v20, v50
	v_mul_f32_e32 v49, v25, v49
	v_mul_f32_e32 v50, v21, v50
	v_cvt_pk_bf16_f32 v51, v51, v56
	v_cvt_pk_bf16_f32 v49, v49, v50
	ds_write2_b32 v52, v51, v49 offset0:130 offset1:195
	v_mov_b32_e32 v49, v247
.LBB0_138:
	v_mul_f32_e32 v50, 0x3e0293ee, v48
	v_mul_f32_e32 v51, 0x3e0293ee, v49
	v_cndmask_b32_e64 v48, v48, v50, s[62:63]
	v_cndmask_b32_e64 v49, v49, v51, s[62:63]
	v_mul_f32_e32 v50, v30, v48
	v_mul_f32_e32 v51, v26, v49
	v_cvt_pk_bf16_f32 v50, v50, v51
	v_mul_f32_e32 v51, v31, v48
	v_mul_f32_e32 v56, v27, v49
	v_cvt_pk_bf16_f32 v51, v51, v56
	ds_write2_b32 v53, v50, v51 offset1:65
	v_mul_f32_e32 v50, v32, v48
	v_mul_f32_e32 v51, v28, v49
	v_mul_f32_e32 v48, v33, v48
	v_mul_f32_e32 v49, v29, v49
	s_add_i32 s14, s24, s27
	v_cvt_pk_bf16_f32 v50, v50, v51
	v_cvt_pk_bf16_f32 v48, v48, v49
	s_mov_b64 s[68:69], s[8:9]
	s_mov_b32 s10, s13
	ds_write2_b32 v53, v50, v48 offset0:130 offset1:195
	v_mov_b32_e32 v240, 1.0
	v_mov_b32_e32 v241, 1.0
	v_mov_b32_e32 v242, 1.0
	v_mov_b32_e32 v243, 1.0
	s_cmp_eq_u64 s[4:5], 0
	s_cbranch_scc1 .Lcv_pre_a
	v_lshl_add_u64 v[238:239], v[42:43], 2, s[4:5]
	global_load_dwordx2 v[240:241], v[238:239], off
	v_lshl_add_u64 v[238:239], v[46:47], 2, s[4:5]
	global_load_dwordx2 v[242:243], v[238:239], off
.Lcv_pre_a:
	s_cmpk_gt_i32 s14, 0x5bff
	s_cbranch_scc1 .Lcv_skip_b
	s_cmpk_gt_i32 s14, 0xbff
	s_mov_b64 s[70:71], -1
	s_cbranch_scc0 .LBB0_165
	s_cmpk_gt_u32 s14, 0xfff
	s_cbranch_scc0 .LBB0_162
	s_cmpk_gt_u32 s14, 0x2fff
	s_cbranch_scc0 .LBB0_159
	s_cmpk_gt_u32 s14, 0x4fff
	s_cbranch_scc0 .LBB0_156
	s_cmpk_gt_u32 s14, 0x51ff
	s_cbranch_scc0 .LBB0_153
	s_add_i32 s29, s33, s15
	s_cmpk_gt_u32 s14, 0x55ff
	s_cbranch_scc0 .LBB0_167
	s_cmpk_gt_u32 s14, 0x57ff
	s_mov_b64 s[64:65], -1
	s_cbranch_scc0 .LBB0_147
	s_add_i32 s10, s14, 0xffffa800
	s_lshr_b32 s10, s10, 9
	v_readlane_b32 s68, v250, 0
	s_and_b32 s27, s14, 0x1ff
	s_lshl_b64 s[38:39], s[10:11], 24
	v_readlane_b32 s76, v250, 8
	v_readlane_b32 s77, v250, 9
	s_add_u32 s62, s76, s38
	s_addc_u32 s63, s77, s39
	s_lshl_b64 s[38:39], s[10:11], 23
	s_add_u32 s58, s16, s38
	v_readlane_b32 s69, v250, 1
	v_readlane_b32 s70, v250, 2
	v_readlane_b32 s71, v250, 3
	v_readlane_b32 s72, v250, 4
	v_readlane_b32 s73, v250, 5
	v_readlane_b32 s74, v250, 6
	v_readlane_b32 s75, v250, 7
	v_readlane_b32 s78, v250, 10
	v_readlane_b32 s79, v250, 11
	v_readlane_b32 s80, v250, 12
	v_readlane_b32 s81, v250, 13
	v_readlane_b32 s82, v250, 14
	v_readlane_b32 s83, v250, 15
	s_addc_u32 s59, s17, s39
	s_mov_b64 s[64:65], 0

.LBB0_275:
	s_mov_b64 s[10:11], 0
	s_add_u32 s10, s96, s10
	s_addc_u32 s11, s97, s11
	s_lshl_b32 s41, s16, 8
	s_lshl_b32 s16, s92, 8
	s_add_i32 s41, s41, s13
	s_or_b32 s40, s16, s25
	v_or_b32_e32 v200, s41, v191
	v_or_b32_e32 v202, s40, v220
	s_mov_b64 s[34:35], -1
	s_mov_b64 s[16:17], 0
	s_cmp_lt_i32 s75, 3
	s_mov_b64 s[20:21], 0
	v_readlane_b32 s24, v250, 39
	s_cbranch_scc1 .LBB0_346
	s_cmp_eq_u32 s75, 3
	s_mov_b64 s[20:21], -1
	s_cbranch_scc0 .LBB0_294
	v_ashrrev_i32_e32 v203, 31, v202
	v_lshl_add_u64 v[130:131], v[202:203], 1, s[10:11]
	s_mov_b64 s[20:21], 0x1b020000
	v_ashrrev_i32_e32 v201, 31, v200
	v_lshl_add_u64 v[130:131], v[130:131], 0, s[20:21]
	v_lshlrev_b64 v[132:133], 12, v[200:201]
	v_lshl_add_u64 v[218:219], v[130:131], 0, v[132:133]
	global_load_dwordx4 v[224:227], v[218:219], off
	global_load_dwordx4 v[186:189], v[218:219], off offset:256
	v_or_b32_e32 v132, 16, v200
	v_ashrrev_i32_e32 v133, 31, v132
	v_lshlrev_b64 v[132:133], 12, v[132:133]
	v_lshl_add_u64 v[216:217], v[130:131], 0, v[132:133]
	v_or_b32_e32 v132, 32, v200
	v_ashrrev_i32_e32 v133, 31, v132
	v_lshlrev_b64 v[132:133], 12, v[132:133]
	v_lshl_add_u64 v[214:215], v[130:131], 0, v[132:133]
	v_or_b32_e32 v132, 48, v200
	v_ashrrev_i32_e32 v133, 31, v132
	v_lshlrev_b64 v[132:133], 12, v[132:133]
	s_mov_b32 s18, 0x80000
	v_lshl_add_u64 v[212:213], v[130:131], 0, v[132:133]
	v_add_co_u32_e32 v130, vcc, s18, v218
	s_mov_b64 s[20:21], 0x80000
	s_nop 0
	v_addc_co_u32_e32 v131, vcc, 0, v219, vcc
	s_mov_b32 s18, 0x90000
	global_load_dwordx4 v[182:185], v[216:217], off
	global_load_dwordx4 v[178:181], v[216:217], off offset:256
	global_load_dwordx4 v[174:177], v[214:215], off
	global_load_dwordx4 v[170:173], v[214:215], off offset:256
	global_load_dwordx4 v[166:169], v[212:213], off
	global_load_dwordx4 v[162:165], v[212:213], off offset:256
	v_lshl_add_u64 v[210:211], v[218:219], 0, s[20:21]
	global_load_dwordx4 v[158:161], v[130:131], off
	global_load_dwordx4 v[154:157], v[210:211], off offset:256
	v_add_co_u32_e32 v130, vcc, s18, v218
	s_mov_b64 s[20:21], 0x90000
	s_nop 0
	v_addc_co_u32_e32 v131, vcc, 0, v219, vcc
	s_mov_b32 s18, 0xa0000
	v_lshl_add_u64 v[208:209], v[218:219], 0, s[20:21]
	global_load_dwordx4 v[150:153], v[130:131], off
	global_load_dwordx4 v[146:149], v[208:209], off offset:256
	v_add_co_u32_e32 v130, vcc, s18, v218
	s_mov_b64 s[20:21], 0xa0000
	s_nop 0
	v_addc_co_u32_e32 v131, vcc, 0, v219, vcc
	s_mov_b32 s18, 0xb0000
	v_lshl_add_u64 v[206:207], v[218:219], 0, s[20:21]
	global_load_dwordx4 v[142:145], v[130:131], off
	global_load_dwordx4 v[138:141], v[206:207], off offset:256
	v_add_co_u32_e32 v130, vcc, s18, v218
	s_mov_b64 s[20:21], 0xb0000
	s_nop 0
	v_addc_co_u32_e32 v131, vcc, 0, v219, vcc
	v_lshl_add_u64 v[204:205], v[218:219], 0, s[20:21]
	global_load_dwordx4 v[134:137], v[130:131], off
	s_nop 0
	global_load_dwordx4 v[130:133], v[204:205], off offset:256
	v_and_b32_e32 v203, 64, v234
	v_xor_b32_e32 v0, 16, v234
	v_add_u32_e32 v203, 64, v203
	v_cmp_lt_i32_e32 vcc, v0, v203
	v_xor_b32_e32 v223, 32, v234
	v_readlane_b32 s20, v249, 9
	v_cndmask_b32_e32 v0, v234, v0, vcc
	v_cmp_lt_i32_e32 vcc, v223, v203
	v_lshlrev_b32_e32 v0, 2, v0
	v_readlane_b32 s21, v249, 10
	v_cndmask_b32_e32 v203, v234, v223, vcc
	v_lshlrev_b32_e32 v203, 2, v203
	s_waitcnt vmcnt(0)
	v_lshlrev_b32_e32 v228, 16, v224
	v_and_b32_e32 v229, 0xffff0000, v224
	v_lshlrev_b32_e32 v224, 16, v225
	v_and_b32_e32 v225, 0xffff0000, v225
	v_lshlrev_b32_e32 v240, 16, v226
	v_and_b32_e32 v241, 0xffff0000, v226
	v_lshlrev_b32_e32 v226, 16, v227
	v_and_b32_e32 v227, 0xffff0000, v227
	v_pk_add_f32 v[242:243], v[128:129], v[224:225]
	v_pk_add_f32 v[228:229], v[126:127], v[228:229]
	v_pk_add_f32 v[244:245], v[124:125], v[226:227]
	v_pk_add_f32 v[240:241], v[122:123], v[240:241]
	v_cvt_pk_bf16_f32 v224, v228, v229
	v_cvt_pk_bf16_f32 v225, v242, v243
	v_cvt_pk_bf16_f32 v226, v240, v241
	v_cvt_pk_bf16_f32 v227, v244, v245
	global_store_dwordx4 v[218:219], v[224:227], off
	v_mul_f32_e32 v223, v229, v229
	v_fmac_f32_e32 v223, v228, v228
	v_mul_f32_e32 v224, v243, v243
	v_fmac_f32_e32 v224, v242, v242
	v_add_f32_e32 v223, v223, v224
	v_mul_f32_e32 v224, v241, v241
	v_fmac_f32_e32 v224, v240, v240
	v_add_f32_e32 v223, v224, v223
	v_mul_f32_e32 v224, v245, v245
	v_fmac_f32_e32 v224, v244, v244
	v_add_f32_e32 v223, v224, v223
	v_lshlrev_b32_e32 v224, 16, v186
	v_and_b32_e32 v225, 0xffff0000, v186
	v_lshlrev_b32_e32 v186, 16, v187
	v_and_b32_e32 v187, 0xffff0000, v187
	v_lshlrev_b32_e32 v226, 16, v188
	v_and_b32_e32 v227, 0xffff0000, v188
	v_lshlrev_b32_e32 v188, 16, v189
	v_and_b32_e32 v189, 0xffff0000, v189
	v_pk_add_f32 v[228:229], v[64:65], v[186:187]
	v_pk_add_f32 v[224:225], v[62:63], v[224:225]
	v_pk_add_f32 v[240:241], v[60:61], v[188:189]
	v_pk_add_f32 v[226:227], v[58:59], v[226:227]
	v_cvt_pk_bf16_f32 v186, v224, v225
	v_cvt_pk_bf16_f32 v187, v228, v229
	v_cvt_pk_bf16_f32 v188, v226, v227
	v_cvt_pk_bf16_f32 v189, v240, v241
	global_store_dwordx4 v[218:219], v[186:189], off offset:256
	s_nop 1
	v_mul_f32_e32 v186, v225, v225
	v_mul_f32_e32 v187, v229, v229
	v_fmac_f32_e32 v186, v224, v224
	v_fmac_f32_e32 v187, v228, v228
	v_add_f32_e32 v186, v186, v187
	v_mul_f32_e32 v187, v227, v227
	v_fmac_f32_e32 v187, v226, v226
	v_add_f32_e32 v186, v187, v186
	v_mul_f32_e32 v187, v241, v241
	v_fmac_f32_e32 v187, v240, v240
	v_add_f32_e32 v186, v187, v186
	v_add_f32_e32 v186, v223, v186
	ds_bpermute_b32 v187, v0, v186
	s_waitcnt lgkmcnt(0)
	v_add_f32_e32 v188, v186, v187
	ds_bpermute_b32 v189, v203, v188
	v_lshl_add_u64 v[186:187], v[200:201], 3, s[20:21]
	s_and_saveexec_b64 s[20:21], s[0:1]
	s_cbranch_execz .LBB0_279
	s_waitcnt lgkmcnt(0)
	v_add_f32_e32 v188, v188, v189
	s_mov_b32 s18, 0x4b800000
	v_fma_f32 v188, v188, s18, 0.5
	v_trunc_f32_e32 v188, v188
	v_mul_f32_e32 v189, 0x2f800000, v188
	v_floor_f32_e32 v189, v189
	v_fmac_f32_e32 v188, 0xcf800000, v189
	v_cvt_u32_f32_e32 v188, v188
	v_cvt_u32_f32_e32 v189, v189
	global_atomic_add_x2 v[186:187], v[188:189], off
.LBB0_279:
	s_or_b64 exec, exec, s[20:21]
	v_lshlrev_b32_e32 v188, 16, v182
	s_waitcnt lgkmcnt(0)
	v_and_b32_e32 v189, 0xffff0000, v182
	v_lshlrev_b32_e32 v182, 16, v183
	v_and_b32_e32 v183, 0xffff0000, v183
	v_lshlrev_b32_e32 v218, 16, v184
	v_and_b32_e32 v219, 0xffff0000, v184
	v_lshlrev_b32_e32 v184, 16, v185
	v_and_b32_e32 v185, 0xffff0000, v185
	v_pk_add_f32 v[224:225], v[120:121], v[182:183]
	v_pk_add_f32 v[188:189], v[118:119], v[188:189]
	v_pk_add_f32 v[226:227], v[116:117], v[184:185]
	v_pk_add_f32 v[218:219], v[114:115], v[218:219]
	v_cvt_pk_bf16_f32 v182, v188, v189
	v_cvt_pk_bf16_f32 v183, v224, v225
	v_cvt_pk_bf16_f32 v184, v218, v219
	v_cvt_pk_bf16_f32 v185, v226, v227
	global_store_dwordx4 v[216:217], v[182:185], off
	s_nop 1
	v_mul_f32_e32 v182, v189, v189
	v_mul_f32_e32 v183, v225, v225
	v_fmac_f32_e32 v182, v188, v188
	v_fmac_f32_e32 v183, v224, v224
	v_add_f32_e32 v182, v182, v183
	v_mul_f32_e32 v183, v219, v219
	v_fmac_f32_e32 v183, v218, v218
	v_add_f32_e32 v182, v183, v182
	v_mul_f32_e32 v183, v227, v227
	v_fmac_f32_e32 v183, v226, v226
	v_add_f32_e32 v201, v183, v182
	v_lshlrev_b32_e32 v182, 16, v178
	v_and_b32_e32 v183, 0xffff0000, v178
	v_lshlrev_b32_e32 v178, 16, v179
	v_and_b32_e32 v179, 0xffff0000, v179
	v_lshlrev_b32_e32 v184, 16, v180
	v_and_b32_e32 v185, 0xffff0000, v180
	v_lshlrev_b32_e32 v180, 16, v181
	v_and_b32_e32 v181, 0xffff0000, v181
	v_pk_add_f32 v[188:189], v[56:57], v[178:179]
	v_pk_add_f32 v[182:183], v[54:55], v[182:183]
	v_pk_add_f32 v[218:219], v[52:53], v[180:181]
	v_pk_add_f32 v[184:185], v[50:51], v[184:185]
	v_cvt_pk_bf16_f32 v178, v182, v183
	v_cvt_pk_bf16_f32 v179, v188, v189
	v_cvt_pk_bf16_f32 v180, v184, v185
	v_cvt_pk_bf16_f32 v181, v218, v219
	global_store_dwordx4 v[216:217], v[178:181], off offset:256
	s_nop 1
	v_mul_f32_e32 v178, v183, v183
	v_mul_f32_e32 v179, v189, v189
	v_fmac_f32_e32 v178, v182, v182
	v_fmac_f32_e32 v179, v188, v188
	v_add_f32_e32 v178, v178, v179
	v_mul_f32_e32 v179, v185, v185
	v_fmac_f32_e32 v179, v184, v184
	v_add_f32_e32 v178, v179, v178
	v_mul_f32_e32 v179, v219, v219
	v_fmac_f32_e32 v179, v218, v218
	v_add_f32_e32 v178, v179, v178
	v_add_f32_e32 v178, v201, v178
	ds_bpermute_b32 v179, v0, v178
	s_waitcnt lgkmcnt(0)
	v_add_f32_e32 v178, v178, v179
	ds_bpermute_b32 v179, v203, v178
	s_and_saveexec_b64 s[20:21], s[0:1]
	s_cbranch_execz .LBB0_281
	s_waitcnt lgkmcnt(0)
	v_add_f32_e32 v178, v178, v179
	s_mov_b32 s18, 0x4b800000
	v_fma_f32 v178, v178, s18, 0.5
	v_trunc_f32_e32 v178, v178
	v_mul_f32_e32 v179, 0x2f800000, v178
	v_floor_f32_e32 v179, v179
	v_fmac_f32_e32 v178, 0xcf800000, v179
	v_cvt_u32_f32_e32 v178, v178
	v_cvt_u32_f32_e32 v179, v179
	global_atomic_add_x2 v[186:187], v[178:179], off offset:128
.LBB0_281:
	s_or_b64 exec, exec, s[20:21]
	v_lshlrev_b32_e32 v178, 16, v174
	s_waitcnt lgkmcnt(0)
	v_and_b32_e32 v179, 0xffff0000, v174
	v_lshlrev_b32_e32 v174, 16, v175
	v_and_b32_e32 v175, 0xffff0000, v175
	v_lshlrev_b32_e32 v180, 16, v176
	v_and_b32_e32 v181, 0xffff0000, v176
	v_lshlrev_b32_e32 v176, 16, v177
	v_and_b32_e32 v177, 0xffff0000, v177
	v_pk_add_f32 v[182:183], v[112:113], v[174:175]
	v_pk_add_f32 v[178:179], v[110:111], v[178:179]
	v_pk_add_f32 v[184:185], v[108:109], v[176:177]
	v_pk_add_f32 v[180:181], v[106:107], v[180:181]
	v_cvt_pk_bf16_f32 v174, v178, v179
	v_cvt_pk_bf16_f32 v175, v182, v183
	v_cvt_pk_bf16_f32 v176, v180, v181
	v_cvt_pk_bf16_f32 v177, v184, v185
	global_store_dwordx4 v[214:215], v[174:177], off
	s_nop 1
	v_mul_f32_e32 v174, v179, v179
	v_mul_f32_e32 v175, v183, v183
	v_fmac_f32_e32 v174, v178, v178
	v_fmac_f32_e32 v175, v182, v182
	v_add_f32_e32 v174, v174, v175
	v_mul_f32_e32 v175, v181, v181
	v_fmac_f32_e32 v175, v180, v180
	v_add_f32_e32 v174, v175, v174
	v_mul_f32_e32 v175, v185, v185
	v_fmac_f32_e32 v175, v184, v184
	v_add_f32_e32 v182, v175, v174
	v_lshlrev_b32_e32 v174, 16, v170
	v_and_b32_e32 v175, 0xffff0000, v170
	v_lshlrev_b32_e32 v170, 16, v171
	v_and_b32_e32 v171, 0xffff0000, v171
	v_lshlrev_b32_e32 v176, 16, v172
	v_and_b32_e32 v177, 0xffff0000, v172
	v_lshlrev_b32_e32 v172, 16, v173
	v_and_b32_e32 v173, 0xffff0000, v173
	v_pk_add_f32 v[178:179], v[48:49], v[170:171]
	v_pk_add_f32 v[174:175], v[46:47], v[174:175]
	v_pk_add_f32 v[180:181], v[44:45], v[172:173]
	v_pk_add_f32 v[176:177], v[42:43], v[176:177]
	v_cvt_pk_bf16_f32 v170, v174, v175
	v_cvt_pk_bf16_f32 v171, v178, v179
	v_cvt_pk_bf16_f32 v172, v176, v177
	v_cvt_pk_bf16_f32 v173, v180, v181
	global_store_dwordx4 v[214:215], v[170:173], off offset:256
	s_nop 1
	v_mul_f32_e32 v170, v175, v175
	v_mul_f32_e32 v171, v179, v179
	v_fmac_f32_e32 v170, v174, v174
	v_fmac_f32_e32 v171, v178, v178
	v_add_f32_e32 v170, v170, v171
	v_mul_f32_e32 v171, v177, v177
	v_fmac_f32_e32 v171, v176, v176
	v_add_f32_e32 v170, v171, v170
	v_mul_f32_e32 v171, v181, v181
	v_fmac_f32_e32 v171, v180, v180
	v_add_f32_e32 v170, v171, v170
	v_add_f32_e32 v170, v182, v170
	ds_bpermute_b32 v171, v0, v170
	s_waitcnt lgkmcnt(0)
	v_add_f32_e32 v170, v170, v171
	ds_bpermute_b32 v171, v203, v170
	s_and_saveexec_b64 s[20:21], s[0:1]
	s_cbranch_execz .LBB0_283
	s_waitcnt lgkmcnt(0)
	v_add_f32_e32 v170, v170, v171
	s_mov_b32 s18, 0x4b800000
	v_fma_f32 v170, v170, s18, 0.5
	v_trunc_f32_e32 v170, v170
	v_mul_f32_e32 v171, 0x2f800000, v170
	v_floor_f32_e32 v171, v171
	v_fmac_f32_e32 v170, 0xcf800000, v171
	v_cvt_u32_f32_e32 v170, v170
	v_cvt_u32_f32_e32 v171, v171
	global_atomic_add_x2 v[186:187], v[170:171], off offset:256
.LBB0_283:
	s_or_b64 exec, exec, s[20:21]
	v_lshlrev_b32_e32 v170, 16, v166
	s_waitcnt lgkmcnt(0)
	v_and_b32_e32 v171, 0xffff0000, v166
	v_lshlrev_b32_e32 v166, 16, v167
	v_and_b32_e32 v167, 0xffff0000, v167
	v_lshlrev_b32_e32 v172, 16, v168
	v_and_b32_e32 v173, 0xffff0000, v168
	v_lshlrev_b32_e32 v168, 16, v169
	v_and_b32_e32 v169, 0xffff0000, v169
	v_pk_add_f32 v[174:175], v[104:105], v[166:167]
	v_pk_add_f32 v[170:171], v[102:103], v[170:171]
	v_pk_add_f32 v[176:177], v[100:101], v[168:169]
	v_pk_add_f32 v[172:173], v[98:99], v[172:173]
	v_cvt_pk_bf16_f32 v166, v170, v171
	v_cvt_pk_bf16_f32 v167, v174, v175
	v_cvt_pk_bf16_f32 v168, v172, v173
	v_cvt_pk_bf16_f32 v169, v176, v177
	global_store_dwordx4 v[212:213], v[166:169], off
	s_nop 1
	v_mul_f32_e32 v166, v171, v171
	v_mul_f32_e32 v167, v175, v175
	v_fmac_f32_e32 v166, v170, v170
	v_fmac_f32_e32 v167, v174, v174
	v_add_f32_e32 v166, v166, v167
	v_mul_f32_e32 v167, v173, v173
	v_fmac_f32_e32 v167, v172, v172
	v_add_f32_e32 v166, v167, v166
	v_mul_f32_e32 v167, v177, v177
	v_fmac_f32_e32 v167, v176, v176
	v_add_f32_e32 v174, v167, v166
	v_lshlrev_b32_e32 v166, 16, v162
	v_and_b32_e32 v167, 0xffff0000, v162
	v_lshlrev_b32_e32 v162, 16, v163
	v_and_b32_e32 v163, 0xffff0000, v163
	v_lshlrev_b32_e32 v168, 16, v164
	v_and_b32_e32 v169, 0xffff0000, v164
	v_lshlrev_b32_e32 v164, 16, v165
	v_and_b32_e32 v165, 0xffff0000, v165
	v_pk_add_f32 v[170:171], v[40:41], v[162:163]
	v_pk_add_f32 v[166:167], v[38:39], v[166:167]
	v_pk_add_f32 v[172:173], v[36:37], v[164:165]
	v_pk_add_f32 v[168:169], v[34:35], v[168:169]
	v_cvt_pk_bf16_f32 v162, v166, v167
	v_cvt_pk_bf16_f32 v163, v170, v171
	v_cvt_pk_bf16_f32 v164, v168, v169
	v_cvt_pk_bf16_f32 v165, v172, v173
	global_store_dwordx4 v[212:213], v[162:165], off offset:256
	s_nop 1
	v_mul_f32_e32 v162, v167, v167
	v_mul_f32_e32 v163, v171, v171
	v_fmac_f32_e32 v162, v166, v166
	v_fmac_f32_e32 v163, v170, v170
	v_add_f32_e32 v162, v162, v163
	v_mul_f32_e32 v163, v169, v169
	v_fmac_f32_e32 v163, v168, v168
	v_add_f32_e32 v162, v163, v162
	v_mul_f32_e32 v163, v173, v173
	v_fmac_f32_e32 v163, v172, v172
	v_add_f32_e32 v162, v163, v162
	v_add_f32_e32 v162, v174, v162
	ds_bpermute_b32 v163, v0, v162
	s_waitcnt lgkmcnt(0)
	v_add_f32_e32 v162, v162, v163
	ds_bpermute_b32 v163, v203, v162
	s_and_saveexec_b64 s[20:21], s[0:1]
	s_cbranch_execz .LBB0_285
	s_waitcnt lgkmcnt(0)
	v_add_f32_e32 v162, v162, v163
	s_mov_b32 s18, 0x4b800000
	v_fma_f32 v162, v162, s18, 0.5
	v_trunc_f32_e32 v162, v162
	v_mul_f32_e32 v163, 0x2f800000, v162
	v_floor_f32_e32 v163, v163
	v_fmac_f32_e32 v162, 0xcf800000, v163
	v_cvt_u32_f32_e32 v162, v162
	v_cvt_u32_f32_e32 v163, v163
	global_atomic_add_x2 v[186:187], v[162:163], off offset:384
.LBB0_285:
	s_or_b64 exec, exec, s[20:21]
	v_lshlrev_b32_e32 v162, 16, v158
	s_waitcnt lgkmcnt(0)
	v_and_b32_e32 v163, 0xffff0000, v158
	v_lshlrev_b32_e32 v158, 16, v159
	v_and_b32_e32 v159, 0xffff0000, v159
	v_lshlrev_b32_e32 v164, 16, v160
	v_and_b32_e32 v165, 0xffff0000, v160
	v_lshlrev_b32_e32 v160, 16, v161
	v_and_b32_e32 v161, 0xffff0000, v161
	v_pk_add_f32 v[166:167], v[96:97], v[158:159]
	v_pk_add_f32 v[162:163], v[94:95], v[162:163]
	v_pk_add_f32 v[168:169], v[92:93], v[160:161]
	v_pk_add_f32 v[164:165], v[90:91], v[164:165]
	v_cvt_pk_bf16_f32 v158, v162, v163
	v_cvt_pk_bf16_f32 v159, v166, v167
	v_cvt_pk_bf16_f32 v160, v164, v165
	v_cvt_pk_bf16_f32 v161, v168, v169
	global_store_dwordx4 v[210:211], v[158:161], off
	s_nop 1
	v_mul_f32_e32 v158, v163, v163
	v_mul_f32_e32 v159, v167, v167
	v_fmac_f32_e32 v158, v162, v162
	v_fmac_f32_e32 v159, v166, v166
	v_add_f32_e32 v158, v158, v159
	v_mul_f32_e32 v159, v165, v165
	v_fmac_f32_e32 v159, v164, v164
	v_add_f32_e32 v158, v159, v158
	v_mul_f32_e32 v159, v169, v169
	v_fmac_f32_e32 v159, v168, v168
	v_add_f32_e32 v166, v159, v158
	v_lshlrev_b32_e32 v158, 16, v154
	v_and_b32_e32 v159, 0xffff0000, v154
	v_lshlrev_b32_e32 v154, 16, v155
	v_and_b32_e32 v155, 0xffff0000, v155
	v_lshlrev_b32_e32 v160, 16, v156
	v_and_b32_e32 v161, 0xffff0000, v156
	v_lshlrev_b32_e32 v156, 16, v157
	v_and_b32_e32 v157, 0xffff0000, v157
	v_pk_add_f32 v[162:163], v[32:33], v[154:155]
	v_pk_add_f32 v[158:159], v[30:31], v[158:159]
	v_pk_add_f32 v[164:165], v[28:29], v[156:157]
	v_pk_add_f32 v[160:161], v[26:27], v[160:161]
	v_cvt_pk_bf16_f32 v154, v158, v159
	v_cvt_pk_bf16_f32 v155, v162, v163
	v_cvt_pk_bf16_f32 v156, v160, v161
	v_cvt_pk_bf16_f32 v157, v164, v165
	global_store_dwordx4 v[210:211], v[154:157], off offset:256
	s_nop 1
	v_mul_f32_e32 v154, v159, v159
	v_mul_f32_e32 v155, v163, v163
	v_fmac_f32_e32 v154, v158, v158
	v_fmac_f32_e32 v155, v162, v162
	v_add_f32_e32 v154, v154, v155
	v_mul_f32_e32 v155, v161, v161
	v_fmac_f32_e32 v155, v160, v160
	v_add_f32_e32 v154, v155, v154
	v_mul_f32_e32 v155, v165, v165
	v_fmac_f32_e32 v155, v164, v164
	v_add_f32_e32 v154, v155, v154
	v_add_f32_e32 v154, v166, v154
	ds_bpermute_b32 v155, v0, v154
	s_waitcnt lgkmcnt(0)
	v_add_f32_e32 v154, v154, v155
	ds_bpermute_b32 v155, v203, v154
	s_and_saveexec_b64 s[20:21], s[0:1]
	s_cbranch_execz .LBB0_287
	s_waitcnt lgkmcnt(0)
	v_add_f32_e32 v154, v154, v155
	s_mov_b32 s18, 0x4b800000
	v_fma_f32 v154, v154, s18, 0.5
	v_trunc_f32_e32 v154, v154
	v_mul_f32_e32 v155, 0x2f800000, v154
	v_floor_f32_e32 v155, v155
	v_fmac_f32_e32 v154, 0xcf800000, v155
	v_cvt_u32_f32_e32 v154, v154
	v_cvt_u32_f32_e32 v155, v155
	global_atomic_add_x2 v[186:187], v[154:155], off offset:1024
.LBB0_287:
	s_or_b64 exec, exec, s[20:21]
	v_lshlrev_b32_e32 v154, 16, v150
	s_waitcnt lgkmcnt(0)
	v_and_b32_e32 v155, 0xffff0000, v150
	v_lshlrev_b32_e32 v150, 16, v151
	v_and_b32_e32 v151, 0xffff0000, v151
	v_lshlrev_b32_e32 v156, 16, v152
	v_and_b32_e32 v157, 0xffff0000, v152
	v_lshlrev_b32_e32 v152, 16, v153
	v_and_b32_e32 v153, 0xffff0000, v153
	v_pk_add_f32 v[158:159], v[88:89], v[150:151]
	v_pk_add_f32 v[154:155], v[86:87], v[154:155]
	v_pk_add_f32 v[160:161], v[84:85], v[152:153]
	v_pk_add_f32 v[156:157], v[82:83], v[156:157]
	v_cvt_pk_bf16_f32 v150, v154, v155
	v_cvt_pk_bf16_f32 v151, v158, v159
	v_cvt_pk_bf16_f32 v152, v156, v157
	v_cvt_pk_bf16_f32 v153, v160, v161
	global_store_dwordx4 v[208:209], v[150:153], off
	s_nop 1
	v_mul_f32_e32 v150, v155, v155
	v_mul_f32_e32 v151, v159, v159
	v_fmac_f32_e32 v150, v154, v154
	v_fmac_f32_e32 v151, v158, v158
	v_add_f32_e32 v150, v150, v151
	v_mul_f32_e32 v151, v157, v157
	v_fmac_f32_e32 v151, v156, v156
	v_add_f32_e32 v150, v151, v150
	v_mul_f32_e32 v151, v161, v161
	v_fmac_f32_e32 v151, v160, v160
	v_add_f32_e32 v158, v151, v150
	v_lshlrev_b32_e32 v150, 16, v146
	v_and_b32_e32 v151, 0xffff0000, v146
	v_lshlrev_b32_e32 v146, 16, v147
	v_and_b32_e32 v147, 0xffff0000, v147
	v_lshlrev_b32_e32 v152, 16, v148
	v_and_b32_e32 v153, 0xffff0000, v148
	v_lshlrev_b32_e32 v148, 16, v149
	v_and_b32_e32 v149, 0xffff0000, v149
	v_pk_add_f32 v[154:155], v[24:25], v[146:147]
	v_pk_add_f32 v[150:151], v[22:23], v[150:151]
	v_pk_add_f32 v[156:157], v[20:21], v[148:149]
	v_pk_add_f32 v[152:153], v[18:19], v[152:153]
	v_cvt_pk_bf16_f32 v146, v150, v151
	v_cvt_pk_bf16_f32 v147, v154, v155
	v_cvt_pk_bf16_f32 v148, v152, v153
	v_cvt_pk_bf16_f32 v149, v156, v157
	global_store_dwordx4 v[208:209], v[146:149], off offset:256
	s_nop 1
	v_mul_f32_e32 v146, v151, v151
	v_mul_f32_e32 v147, v155, v155
	v_fmac_f32_e32 v146, v150, v150
	v_fmac_f32_e32 v147, v154, v154
	v_add_f32_e32 v146, v146, v147
	v_mul_f32_e32 v147, v153, v153
	v_fmac_f32_e32 v147, v152, v152
	v_add_f32_e32 v146, v147, v146
	v_mul_f32_e32 v147, v157, v157
	v_fmac_f32_e32 v147, v156, v156
	v_add_f32_e32 v146, v147, v146
	v_add_f32_e32 v146, v158, v146
	ds_bpermute_b32 v147, v0, v146
	s_waitcnt lgkmcnt(0)
	v_add_f32_e32 v146, v146, v147
	ds_bpermute_b32 v147, v203, v146
	s_and_saveexec_b64 s[20:21], s[0:1]
	s_cbranch_execz .LBB0_289
	s_waitcnt lgkmcnt(0)
	v_add_f32_e32 v146, v146, v147
	s_mov_b32 s18, 0x4b800000
	v_fma_f32 v146, v146, s18, 0.5
	v_trunc_f32_e32 v146, v146
	v_mul_f32_e32 v147, 0x2f800000, v146
	v_floor_f32_e32 v147, v147
	v_fmac_f32_e32 v146, 0xcf800000, v147
	v_cvt_u32_f32_e32 v146, v146
	v_cvt_u32_f32_e32 v147, v147
	global_atomic_add_x2 v[186:187], v[146:147], off offset:1152
.LBB0_289:
	s_or_b64 exec, exec, s[20:21]
	v_lshlrev_b32_e32 v146, 16, v142
	s_waitcnt lgkmcnt(0)
	v_and_b32_e32 v147, 0xffff0000, v142
	v_lshlrev_b32_e32 v142, 16, v143
	v_and_b32_e32 v143, 0xffff0000, v143
	v_lshlrev_b32_e32 v148, 16, v144
	v_and_b32_e32 v149, 0xffff0000, v144
	v_lshlrev_b32_e32 v144, 16, v145
	v_and_b32_e32 v145, 0xffff0000, v145
	v_pk_add_f32 v[150:151], v[80:81], v[142:143]
	v_pk_add_f32 v[146:147], v[78:79], v[146:147]
	v_pk_add_f32 v[152:153], v[76:77], v[144:145]
	v_pk_add_f32 v[148:149], v[74:75], v[148:149]
	v_cvt_pk_bf16_f32 v142, v146, v147
	v_cvt_pk_bf16_f32 v143, v150, v151
	v_cvt_pk_bf16_f32 v144, v148, v149
	v_cvt_pk_bf16_f32 v145, v152, v153
	global_store_dwordx4 v[206:207], v[142:145], off
	s_nop 1
	v_mul_f32_e32 v142, v147, v147
	v_mul_f32_e32 v143, v151, v151
	v_fmac_f32_e32 v142, v146, v146
	v_fmac_f32_e32 v143, v150, v150
	v_add_f32_e32 v142, v142, v143
	v_mul_f32_e32 v143, v149, v149
	v_fmac_f32_e32 v143, v148, v148
	v_add_f32_e32 v142, v143, v142
	v_mul_f32_e32 v143, v153, v153
	v_fmac_f32_e32 v143, v152, v152
	v_add_f32_e32 v150, v143, v142
	v_lshlrev_b32_e32 v142, 16, v138
	v_and_b32_e32 v143, 0xffff0000, v138
	v_lshlrev_b32_e32 v138, 16, v139
	v_and_b32_e32 v139, 0xffff0000, v139
	v_lshlrev_b32_e32 v144, 16, v140
	v_and_b32_e32 v145, 0xffff0000, v140
	v_lshlrev_b32_e32 v140, 16, v141
	v_and_b32_e32 v141, 0xffff0000, v141
	v_pk_add_f32 v[146:147], v[16:17], v[138:139]
	v_pk_add_f32 v[142:143], v[14:15], v[142:143]
	v_pk_add_f32 v[148:149], v[12:13], v[140:141]
	v_pk_add_f32 v[144:145], v[10:11], v[144:145]
	v_cvt_pk_bf16_f32 v138, v142, v143
	v_cvt_pk_bf16_f32 v139, v146, v147
	v_cvt_pk_bf16_f32 v140, v144, v145
	v_cvt_pk_bf16_f32 v141, v148, v149
	global_store_dwordx4 v[206:207], v[138:141], off offset:256
	s_nop 1
	v_mul_f32_e32 v138, v143, v143
	v_mul_f32_e32 v139, v147, v147
	v_fmac_f32_e32 v138, v142, v142
	v_fmac_f32_e32 v139, v146, v146
	v_add_f32_e32 v138, v138, v139
	v_mul_f32_e32 v139, v145, v145
	v_fmac_f32_e32 v139, v144, v144
	v_add_f32_e32 v138, v139, v138
	v_mul_f32_e32 v139, v149, v149
	v_fmac_f32_e32 v139, v148, v148
	v_add_f32_e32 v138, v139, v138
	v_add_f32_e32 v138, v150, v138
	ds_bpermute_b32 v139, v0, v138
	s_waitcnt lgkmcnt(0)
	v_add_f32_e32 v138, v138, v139
	ds_bpermute_b32 v139, v203, v138
	s_and_saveexec_b64 s[20:21], s[0:1]
	s_cbranch_execz .LBB0_291
	s_waitcnt lgkmcnt(0)
	v_add_f32_e32 v138, v138, v139
	s_mov_b32 s18, 0x4b800000
	v_fma_f32 v138, v138, s18, 0.5
	v_trunc_f32_e32 v138, v138
	v_mul_f32_e32 v139, 0x2f800000, v138
	v_floor_f32_e32 v139, v139
	v_fmac_f32_e32 v138, 0xcf800000, v139
	v_cvt_u32_f32_e32 v138, v138
	v_cvt_u32_f32_e32 v139, v139
	global_atomic_add_x2 v[186:187], v[138:139], off offset:1280
.LBB0_291:
	s_or_b64 exec, exec, s[20:21]
	v_lshlrev_b32_e32 v138, 16, v134
	s_waitcnt lgkmcnt(0)
	v_and_b32_e32 v139, 0xffff0000, v134
	v_lshlrev_b32_e32 v134, 16, v135
	v_and_b32_e32 v135, 0xffff0000, v135
	v_lshlrev_b32_e32 v140, 16, v136
	v_and_b32_e32 v141, 0xffff0000, v136
	v_lshlrev_b32_e32 v136, 16, v137
	v_and_b32_e32 v137, 0xffff0000, v137
	v_pk_add_f32 v[142:143], v[72:73], v[134:135]
	v_pk_add_f32 v[138:139], v[70:71], v[138:139]
	v_pk_add_f32 v[144:145], v[68:69], v[136:137]
	v_pk_add_f32 v[140:141], v[66:67], v[140:141]
	v_cvt_pk_bf16_f32 v134, v138, v139
	v_cvt_pk_bf16_f32 v135, v142, v143
	v_cvt_pk_bf16_f32 v136, v140, v141
	v_cvt_pk_bf16_f32 v137, v144, v145
	global_store_dwordx4 v[204:205], v[134:137], off
	s_nop 1
	v_mul_f32_e32 v134, v139, v139
	v_mul_f32_e32 v135, v143, v143
	v_fmac_f32_e32 v134, v138, v138
	v_fmac_f32_e32 v135, v142, v142
	v_add_f32_e32 v134, v134, v135
	v_mul_f32_e32 v135, v141, v141
	v_fmac_f32_e32 v135, v140, v140
	v_add_f32_e32 v134, v135, v134
	v_mul_f32_e32 v135, v145, v145
	v_fmac_f32_e32 v135, v144, v144
	v_add_f32_e32 v142, v135, v134
	v_lshlrev_b32_e32 v134, 16, v130
	v_and_b32_e32 v135, 0xffff0000, v130
	v_lshlrev_b32_e32 v130, 16, v131
	v_and_b32_e32 v131, 0xffff0000, v131
	v_lshlrev_b32_e32 v136, 16, v132
	v_and_b32_e32 v137, 0xffff0000, v132
	v_lshlrev_b32_e32 v132, 16, v133
	v_and_b32_e32 v133, 0xffff0000, v133
	v_pk_add_f32 v[138:139], v[8:9], v[130:131]
	v_pk_add_f32 v[134:135], v[6:7], v[134:135]
	v_pk_add_f32 v[140:141], v[4:5], v[132:133]
	v_pk_add_f32 v[136:137], v[2:3], v[136:137]
	v_cvt_pk_bf16_f32 v130, v134, v135
	v_cvt_pk_bf16_f32 v131, v138, v139
	v_cvt_pk_bf16_f32 v132, v136, v137
	v_cvt_pk_bf16_f32 v133, v140, v141
	global_store_dwordx4 v[204:205], v[130:133], off offset:256
	s_nop 1
	v_mul_f32_e32 v130, v135, v135
	v_mul_f32_e32 v131, v139, v139
	v_fmac_f32_e32 v130, v134, v134
	v_fmac_f32_e32 v131, v138, v138
	v_add_f32_e32 v130, v130, v131
	v_mul_f32_e32 v131, v137, v137
	v_fmac_f32_e32 v131, v136, v136
	v_add_f32_e32 v130, v131, v130
	v_mul_f32_e32 v131, v141, v141
	v_fmac_f32_e32 v131, v140, v140
	v_add_f32_e32 v130, v131, v130
	v_add_f32_e32 v130, v142, v130
	ds_bpermute_b32 v0, v0, v130
	s_waitcnt lgkmcnt(0)
	v_add_f32_e32 v0, v130, v0
	ds_bpermute_b32 v130, v203, v0
	s_and_saveexec_b64 s[20:21], s[0:1]
	s_cbranch_execz .LBB0_293
	s_waitcnt lgkmcnt(0)
	v_add_f32_e32 v0, v0, v130
	s_mov_b32 s18, 0x4b800000
	v_fma_f32 v0, v0, s18, 0.5
	v_trunc_f32_e32 v0, v0
	v_mul_f32_e32 v130, 0x2f800000, v0
	v_floor_f32_e32 v131, v130
	v_fmac_f32_e32 v0, 0xcf800000, v131
	v_cvt_u32_f32_e32 v130, v0
	v_cvt_u32_f32_e32 v131, v131
	global_atomic_add_x2 v[186:187], v[130:131], off offset:1408
